# barriers behind finalize and G3 take an XCD-local form (no L2 write-back, own XCC's arrival counter) when every workgroup is verified to sit on XCC blockIdx%8
# speedup vs baseline: 1.0103x; 1.0103x over previous
.LBB0_7:
	s_add_u32 s0, s4, 0x1000
	s_addc_u32 s1, s5, 0
	v_writelane_b32 v252, s0, 8
	s_mov_b64 s[52:53], 0x1000
	s_mov_b32 s51, 0
	v_writelane_b32 v255, s51, 20
	v_writelane_b32 v252, s1, 9
	s_getreg_b32 s0, hwreg(HW_REG_XCC_ID, 0, 4)
	s_and_b32 s2, s0, 15
	s_lshl_b32 s0, s2, 6
	v_writelane_b32 v252, s0, 10
	s_and_saveexec_b64 s[4:5], s[6:7]
	s_cbranch_execz .LBB0_10
	s_mov_b64 s[6:7], exec
	v_mbcnt_lo_u32_b32 v0, s6, 0
	v_mbcnt_hi_u32_b32 v0, s7, v0
	v_cmp_eq_u32_e32 vcc, 0, v0
	s_and_b64 s[0:1], exec, vcc
	s_mov_b64 exec, s[0:1]
	s_cbranch_execz .LBB0_10
	v_readlane_b32 s0, v252, 10
	s_lshl_b32 s0, s0, 2
	s_bcnt1_i32_b64 s1, s[6:7]
	v_mov_b32_e32 v0, s0
	v_mov_b32_e32 v1, s1
	v_readlane_b32 s0, v252, 8
	v_readlane_b32 s1, v252, 9
	s_nop 4
	global_atomic_add v0, v1, s[0:1] offset:1024
	v_readlane_b32 vcc_lo, v252, 10
	s_and_b32 vcc_hi, s97, 7
	s_lshr_b32 vcc_lo, vcc_lo, 6
	s_cmp_eq_u32 vcc_lo, vcc_hi
	s_cbranch_scc0 .Lplace_bad
	s_cmp_eq_u32 s87, 0x100
	s_cbranch_scc1 .Lplace_ok
.Lplace_bad:
	v_mov_b32_e32 v0, 0x5000
	s_nop 0
	global_atomic_add v0, v1, s[0:1]
.Lplace_ok:
.LBB0_10:
	s_or_b64 exec, exec, s[4:5]
	v_readlane_b32 s6, v252, 2
	s_cmpk_lt_i32 s6, 0x100
	s_cselect_b64 s[0:1], -1, 0
	v_writelane_b32 v252, s0, 11
	s_movk_i32 s64, 0x90
	s_mov_b32 s70, -2.0
	v_writelane_b32 v252, s1, 12
	s_and_b32 s0, s6, 7
	s_lshl_b32 s4, s0, 6
	s_cmpk_gt_i32 s97, 0x7f
	s_cselect_b64 s[8:9], -1, 0
	s_lshl_b32 s1, s97, 1
	s_and_b32 s1, s1, 14
	s_bfe_u32 s3, s97, 0x10006
	s_or_b32 s1, s1, s3
	s_or_b32 s3, s1, 0x90
	v_writelane_b32 v252, s8, 13
	s_cmpk_lt_i32 s97, 0x80
	s_cselect_b32 s3, s1, s3
	v_writelane_b32 v252, s9, 14
	s_cselect_b32 s5, s64, 0x100
	s_or_b32 s1, s4, 0xfffffa00
	v_writelane_b32 v252, s1, 15
	v_writelane_b32 v252, s4, 16
	s_or_b32 s1, s4, 0xfffff600
	v_writelane_b32 v252, s1, 17
	s_lshl_b32 s1, s3, 6
	s_and_b32 s4, s1, 0x7c0
	v_writelane_b32 v252, s4, 18
	s_and_b32 s4, s1, 0x2000
	v_writelane_b32 v252, s4, 19
	v_writelane_b32 v252, s3, 20
	s_cmp_lt_u32 s3, s5
	v_writelane_b32 v252, s5, 21
	s_cselect_b64 s[4:5], -1, 0
	v_writelane_b32 v252, s4, 22
	s_lshl_b32 s3, s0, 9
	s_mov_b32 s88, 0xc1000000
	v_writelane_b32 v252, s5, 23
	v_writelane_b32 v252, s3, 24
	s_lshl_b32 s3, s0, 7
	v_writelane_b32 v252, s3, 25
	s_add_i32 s3, s97, 0xffffff80
	s_add_i32 s4, s87, 0xffffff80
	v_writelane_b32 v252, s4, 26
	s_cmpk_lt_u32 s3, 0x100
	v_writelane_b32 v252, s3, 27
	s_cselect_b64 s[4:5], -1, 0
	v_writelane_b32 v252, s4, 28
	s_mul_i32 s3, s97, 7
	s_mov_b32 s92, 0xc1200000
	v_writelane_b32 v252, s5, 29
	s_mov_b32 s44, 0xc1800000
	v_readlane_b32 s7, v252, 3
	s_add_i32 s24, s7, s3
	s_mul_i32 s3, s7, 0x2400
	s_add_i32 s4, s24, -1
	s_add_i32 s3, s3, 0
	s_cmpk_gt_i32 s24, 0x680
	v_writelane_b32 v252, s3, 30
	s_cselect_b64 s[8:9], -1, 0
	s_add_i32 s3, s24, 0xfffff97f
	s_lshr_b32 s50, s3, 4
	v_writelane_b32 v252, s8, 31
	s_cmp_gt_u32 s3, 31
	s_mov_b32 s12, 0x41000000
	v_writelane_b32 v252, s9, 32
	s_cselect_b64 s[8:9], -1, 0
	v_writelane_b32 v252, s8, 33
	s_lshl_b32 s3, s3, 13
	s_and_b32 s3, s3, 0x20000
	v_writelane_b32 v252, s9, 34
	v_writelane_b32 v252, s3, 35
	s_lshl_b64 s[8:9], s[50:51], 16
	v_writelane_b32 v252, s8, 36
	s_and_b32 s3, s4, 15
	s_mov_b32 s14, 0x41200000
	v_writelane_b32 v252, s9, 37
	v_writelane_b32 v252, s4, 38
	v_writelane_b32 v252, s3, 39
	s_ashr_i32 s4, s97, 1
	s_lshl_b32 s3, s97, 5
	s_and_b32 s3, s3, 32
	s_lshl_b32 s8, s4, 6
	s_cmp_gt_i32 s4, 31
	v_writelane_b32 v252, s3, 40
	s_cselect_b64 s[10:11], -1, 0
	v_writelane_b32 v252, s10, 41
	s_add_i32 s50, s8, 0xfffff800
	s_ashr_i32 s9, s8, 31
	v_writelane_b32 v252, s11, 42
	v_writelane_b32 v252, s50, 43
	s_ashr_i32 s5, s4, 31
	s_lshl_b64 s[4:5], s[4:5], 19
	v_writelane_b32 v252, s51, 44
	v_writelane_b32 v252, s8, 45
	s_cmpk_lt_i32 s97, 0x300
	s_mov_b32 s16, 0x41800000
	v_writelane_b32 v252, s9, 46
	v_writelane_b32 v252, s4, 47
	s_mov_b32 s18, 0x41900000
	s_mov_b32 s20, 0x41c00000
	v_writelane_b32 v252, s5, 48
	s_cselect_b64 s[4:5], -1, 0
	v_writelane_b32 v252, s4, 49
	s_ashr_i32 s3, s97, 31
	s_lshl_b32 s80, s87, 3
	v_writelane_b32 v252, s5, 50
	v_writelane_b32 v252, s3, 51
	s_lshr_b32 s3, s3, 29
	s_ashr_i32 s5, s87, 31
	s_add_i32 s4, s97, s3
	v_writelane_b32 v252, s5, 52
	s_lshl_b32 s5, s6, 3
	s_ashr_i32 s3, s4, 3
	s_and_b32 s4, s4, -8
	v_writelane_b32 v252, s5, 53
	s_add_i32 s6, s5, s7
	s_lshl_b32 s5, s7, 14
	s_sub_i32 s4, s97, s4
	s_add_i32 s5, s5, 0
	s_cmpk_lt_i32 s6, 0x6c0
	v_writelane_b32 v252, s5, 54
	s_cselect_b64 s[8:9], -1, 0
	v_writelane_b32 v252, s8, 55
	s_cmpk_lt_i32 s6, 0x680
	s_mov_b32 s22, 0x41d00000
	v_writelane_b32 v252, s9, 56
	s_cselect_b64 s[8:9], -1, 0
	v_writelane_b32 v252, s8, 57
	s_cmpk_gt_i32 s6, 0x67f
	v_mov_b32_e32 v0, 0
	v_writelane_b32 v252, s9, 58
	s_cselect_b64 s[8:9], -1, 0
	s_add_i32 s5, s6, 0xfffff980
	s_lshr_b32 s50, s5, 4
	v_writelane_b32 v252, s8, 59
	s_cmp_gt_u32 s5, 31
	v_mov_b32_e32 v220, 0x358637bd
	v_writelane_b32 v252, s9, 60
	s_cselect_b64 s[8:9], -1, 0
	v_writelane_b32 v252, s8, 61
	s_lshl_b32 s5, s5, 13
	s_and_b32 s5, s5, 0x20000
	v_writelane_b32 v252, s9, 62
	s_lshl_b64 s[8:9], s[50:51], 16
	v_writelane_b32 v253, s8, 0
	v_writelane_b32 v252, s5, 63
	s_and_b32 s5, s6, 15
	v_writelane_b32 v253, s9, 1
	v_writelane_b32 v253, s6, 2
	s_cmpk_lt_i32 s97, 0x100
	v_writelane_b32 v253, s5, 3
	s_cselect_b64 s[6:7], -1, 0
	s_lshl_b32 s5, s4, 5
	v_writelane_b32 v253, s6, 4
	s_cmpk_lt_i32 s97, 0x400
	v_mov_b32_e32 v221, 0x3a27c5ac
	v_writelane_b32 v253, s7, 5
	s_cselect_b64 s[6:7], -1, 0
	v_writelane_b32 v253, s6, 6
	v_mov_b32_e32 v222, 0x260
	v_mov_b32_e32 v223, 1
	v_writelane_b32 v253, s7, 7
	s_lshl_b32 s6, s4, 7
	s_cmp_eq_u32 s2, 15
	s_cselect_b64 s[8:9], -1, 0
	v_writelane_b32 v253, s8, 8
	s_cmp_eq_u32 s2, 14
	s_mov_b32 s71, 0xc0400000
	v_writelane_b32 v253, s9, 9
	s_cselect_b64 s[8:9], -1, 0
	v_writelane_b32 v253, s8, 10
	s_cmp_eq_u32 s2, 13
	s_mov_b32 s89, 0xc1100000
	v_writelane_b32 v253, s9, 11
	s_cselect_b64 s[8:9], -1, 0
	v_writelane_b32 v253, s8, 12
	s_cmp_eq_u32 s2, 12
	s_mov_b32 s93, 0xc1300000
	v_writelane_b32 v253, s9, 13
	s_cselect_b64 s[8:9], -1, 0
	v_writelane_b32 v253, s8, 14
	s_cmp_eq_u32 s2, 11
	s_mov_b32 s45, 0xc1880000
	v_writelane_b32 v253, s9, 15
	s_cselect_b64 s[8:9], -1, 0
	v_writelane_b32 v253, s8, 16
	s_cmp_eq_u32 s2, 10
	s_mov_b32 s13, 0x41100000
	v_writelane_b32 v253, s9, 17
	s_cselect_b64 s[8:9], -1, 0
	v_writelane_b32 v253, s8, 18
	s_cmp_eq_u32 s2, 9
	s_mov_b32 s15, 0x41300000
	v_writelane_b32 v253, s9, 19
	s_cselect_b64 s[8:9], -1, 0
	v_writelane_b32 v253, s8, 20
	s_cmp_eq_u32 s2, 8
	s_mov_b32 s17, 0x41880000
	v_writelane_b32 v253, s9, 21
	s_cselect_b64 s[8:9], -1, 0
	v_writelane_b32 v253, s8, 22
	s_cmp_eq_u32 s2, 7
	s_mov_b32 s19, 0x41980000
	v_writelane_b32 v253, s9, 23
	s_cselect_b64 s[8:9], -1, 0
	v_writelane_b32 v253, s8, 24
	s_cmp_eq_u32 s2, 6
	s_mov_b32 s21, 0x41c80000
	v_writelane_b32 v253, s9, 25
	s_cselect_b64 s[8:9], -1, 0
	v_writelane_b32 v253, s8, 26
	s_cmp_eq_u32 s2, 5
	s_mov_b32 s23, 0x41d80000
	v_writelane_b32 v253, s9, 27
	s_cselect_b64 s[8:9], -1, 0
	v_writelane_b32 v253, s8, 28
	s_cmp_eq_u32 s2, 4
	v_mov_b32_e32 v224, 0x3f80
	v_writelane_b32 v253, s9, 29
	s_cselect_b64 s[8:9], -1, 0
	v_writelane_b32 v253, s8, 30
	s_cmp_eq_u32 s2, 3
	v_mov_b32_e32 v225, 0xfff
	v_writelane_b32 v253, s9, 31
	s_cselect_b64 s[8:9], -1, 0
	v_writelane_b32 v253, s8, 32
	s_cmp_eq_u32 s2, 2
	v_mov_b32_e32 v226, 0xf149f2ca
	v_writelane_b32 v253, s9, 33
	s_cselect_b64 s[8:9], -1, 0
	v_writelane_b32 v253, s8, 34
	s_cmp_eq_u32 s2, 1
	v_mov_b64_e32 v[194:195], 0x2ff
	v_writelane_b32 v253, s9, 35
	s_cselect_b64 s[8:9], -1, 0
	v_writelane_b32 v253, s8, 36
	s_cmp_eq_u32 s2, 0
	s_mul_i32 s2, s4, 33
	v_writelane_b32 v253, s9, 37
	s_cselect_b64 s[8:9], -1, 0
	s_cmp_lt_i32 s4, 0
	s_cselect_b32 s2, s2, s5
	s_movk_i32 s5, 0x61
	s_cselect_b32 s5, s5, 0x60
	s_mul_i32 s5, s4, s5
	s_mulk_i32 s4, 0x81
	s_cselect_b32 s4, s4, s6
	s_add_i32 s5, s5, s3
	s_mul_hi_i32 s6, s5, 0x2aaaaaab
	s_lshr_b32 s7, s6, 31
	s_ashr_i32 s6, s6, 4
	s_add_i32 s6, s6, s7
	s_mul_i32 s7, s6, 0x60
	s_sub_i32 s5, s5, s7
	s_bfe_i32 s7, s5, 0x80000
	s_bfe_u32 s7, s7, 0x3000c
	v_writelane_b32 v253, s8, 38
	s_add_i32 s7, s5, s7
	s_add_i32 s2, s2, s3
	v_writelane_b32 v253, s9, 39
	s_and_b32 s8, s7, 0xf8
	s_sub_i32 s5, s5, s8
	s_ashr_i32 s8, s2, 31
	s_lshr_b32 s8, s8, 27
	s_add_i32 s8, s2, s8
	s_and_b32 s9, s8, 0xffe0
	s_sub_i32 s2, s2, s9
	s_bfe_i32 s9, s2, 0x80000
	s_add_i32 s3, s4, s3
	s_bfe_u32 s9, s9, 0x3000c
	s_ashr_i32 s4, s3, 31
	s_add_i32 s9, s2, s9
	s_lshr_b32 s4, s4, 25
	s_and_b32 s10, s9, 0xf8
	s_add_i32 s4, s3, s4
	s_sub_i32 s2, s2, s10
	s_and_b32 s10, s4, 0xff80
	s_sub_i32 s3, s3, s10
	s_bfe_i32 s10, s3, 0x80000
	s_bfe_u32 s10, s10, 0x3000c
	s_lshl_b32 s6, s6, 3
	s_sext_i32_i8 s5, s5
	s_add_i32 s10, s3, s10
	s_add_i32 s26, s6, s5
	s_ashr_i32 s5, s8, 5
	s_and_b32 s11, s10, 0xf8
	s_lshl_b32 s5, s5, 3
	s_sext_i32_i8 s2, s2
	s_sub_i32 s3, s3, s11
	s_add_i32 s8, s5, s2
	s_ashr_i32 s2, s4, 7
	s_bfe_i32 s4, s10, 0x80000
	s_lshl_b32 s2, s2, 3
	s_sext_i32_i16 s4, s4
	s_sext_i32_i8 s3, s3
	s_add_i32 s28, s2, s3
	s_ashr_i32 s2, s4, 3
	v_writelane_b32 v253, s2, 40
	s_lshr_b32 s2, s4, 3
	s_bfe_i64 s[2:3], s[2:3], 0x100000
	s_bfe_i32 s7, s7, 0x80000
	s_lshl_b64 s[2:3], s[2:3], 19
	s_sext_i32_i16 s7, s7
	v_writelane_b32 v253, s2, 41
	s_bfe_i32 s6, s9, 0x80000
	s_ashr_i32 s9, s8, 31
	v_writelane_b32 v253, s3, 42
	s_ashr_i32 s2, s7, 3
	v_writelane_b32 v253, s2, 43
	s_lshr_b32 s2, s7, 3
	s_bfe_i64 s[2:3], s[2:3], 0x100000
	s_lshl_b64 s[2:3], s[2:3], 19
	v_writelane_b32 v253, s2, 44
	s_sext_i32_i16 s6, s6
	s_addk_i32 s1, 0x400
	v_writelane_b32 v253, s3, 45
	v_writelane_b32 v253, s8, 46
	s_ashr_i32 s2, s6, 3
	s_lshl_b32 s0, s0, 2
	v_writelane_b32 v253, s9, 47
	v_writelane_b32 v253, s2, 48
	s_lshr_b32 s2, s6, 3
	s_bfe_i64 s[2:3], s[2:3], 0x100000
	v_writelane_b32 v253, s2, 49
	s_ashr_i32 s29, s28, 31
	s_ashr_i32 s27, s26, 31
	v_writelane_b32 v253, s3, 50
	v_writelane_b32 v253, s1, 51
	s_lshl_b32 s1, s97, 6
	s_addk_i32 s1, 0xe000
	v_writelane_b32 v253, s1, 52
	s_lshl_b32 s1, s87, 6
	s_addk_i32 s1, 0xe000
	v_writelane_b32 v253, s1, 53
	v_writelane_b32 v253, s0, 54
	s_lshl_b32 s1, s97, 10
	v_writelane_b32 v253, s24, 55
	s_add_i32 s0, s24, 0xfffffcff
	s_and_b32 s1, s1, 0x400
	v_writelane_b32 v253, s0, 56
	v_writelane_b32 v253, s1, 57
	s_or_b32 s0, s1, 0x800
	v_writelane_b32 v253, s0, 58
	s_lshl_b32 s0, s87, 4
	v_writelane_b32 v253, s0, 59
	s_add_i32 s0, 0, 0x4400
	v_writelane_b32 v253, s0, 60
	s_add_i32 s0, 0, 0x1f800
	v_writelane_b32 v253, s0, 61
	s_add_i32 s0, 0, 0x21c00
	v_writelane_b32 v253, s0, 62
	s_add_i32 s0, 0, 0x25200
	v_writelane_b32 v253, s0, 63
	s_add_i32 s0, 0, 0x25300
	v_writelane_b32 v254, s0, 0
	s_add_i32 s0, 0, 0x26160
	v_writelane_b32 v254, s0, 1
	s_add_i32 s0, 0, 0x26164
	v_writelane_b32 v254, s0, 2
	s_add_i32 s0, 0, 0x1400
	v_writelane_b32 v254, s0, 3
	s_add_i32 s0, 0, 0x1800
	v_writelane_b32 v254, s0, 4
	s_add_i32 s0, 0, 0x2800
	v_writelane_b32 v254, s0, 5
	s_add_i32 s0, 0, 0x2c00
	v_writelane_b32 v254, s0, 6
	s_add_i32 s0, 0, 0x3400
	v_writelane_b32 v254, s0, 7
	s_add_i32 s0, 0, 0x3800
	v_writelane_b32 v254, s0, 8
	s_add_i32 s0, 0, 0x3c00
	v_writelane_b32 v254, s0, 9
	s_add_i32 s0, 0, 0x4800
	v_writelane_b32 v254, s0, 10
	s_add_i32 s0, 0, 0x4c00
	v_writelane_b32 v254, s0, 11
	s_add_i32 s0, 0, 0x5000
	v_writelane_b32 v254, s0, 12
	s_add_i32 s0, 0, 0x5400
	v_writelane_b32 v254, s0, 13
	s_add_i32 s0, 0, 0x5800
	v_writelane_b32 v254, s0, 14
	s_add_i32 s0, 0, 0x5c00
	v_writelane_b32 v254, s0, 15
	s_add_i32 s0, 0, 0x6400
	v_writelane_b32 v254, s0, 16
	s_add_i32 s0, 0, 0x6800
	v_writelane_b32 v254, s0, 17
	s_add_i32 s0, 0, 0x6c00
	v_writelane_b32 v254, s0, 18
	s_add_i32 s0, 0, 0x7000
	v_writelane_b32 v254, s0, 19
	s_add_i32 s0, 0, 0x7400
	v_writelane_b32 v254, s0, 20
	s_add_i32 s0, 0, 0x7800
	v_writelane_b32 v254, s0, 21
	s_add_i32 s0, 0, 0x7c00
	v_writelane_b32 v254, s0, 22
	s_add_i32 s0, 0, 0x8400
	v_writelane_b32 v254, s0, 23
	s_add_i32 s0, 0, 0x8800
	v_writelane_b32 v254, s0, 24
	s_add_i32 s0, 0, 0x8c00
	v_writelane_b32 v254, s0, 25
	s_add_i32 s0, 0, 0x9400
	v_writelane_b32 v254, s0, 26
	s_add_i32 s0, 0, 0x9800
	v_writelane_b32 v254, s0, 27
	s_add_i32 s0, 0, 0x9c00
	v_writelane_b32 v254, s0, 28
	s_add_i32 s0, 0, 0xa400
	v_writelane_b32 v254, s0, 29
	s_add_i32 s0, 0, 0xa800
	v_writelane_b32 v254, s0, 30
	s_add_i32 s0, 0, 0xac00
	v_writelane_b32 v254, s0, 31
	s_add_i32 s0, 0, 0xb000
	v_writelane_b32 v254, s0, 32
	s_add_i32 s0, 0, 0xb800
	v_writelane_b32 v254, s0, 33
	s_add_i32 s0, 0, 0xbc00
	v_writelane_b32 v254, s0, 34
	s_add_i32 s0, 0, 0xc400
	v_writelane_b32 v254, s0, 35
	s_add_i32 s0, 0, 0xc800
	v_writelane_b32 v254, s0, 36
	s_add_i32 s0, 0, 0xcc00
	v_writelane_b32 v254, s0, 37
	s_add_i32 s0, 0, 0xd000
	v_writelane_b32 v254, s0, 38
	s_add_i32 s0, 0, 0xd400
	v_writelane_b32 v254, s0, 39
	s_add_i32 s0, 0, 0xdc00
	v_writelane_b32 v254, s0, 40
	s_add_i32 s0, 0, 0xe400
	v_writelane_b32 v254, s0, 41
	s_add_i32 s0, 0, 0xe800
	v_writelane_b32 v254, s0, 42
	s_add_i32 s0, 0, 0xec00
	v_writelane_b32 v254, s0, 43
	s_lshl_b64 s[0:1], s[28:29], 14
	v_writelane_b32 v254, s0, 44
	s_mov_b32 s4, 0xc1900000
	s_mov_b32 s6, 0xc1c00000
	v_writelane_b32 v254, s1, 45
	s_mov_b32 s0, s28
	v_writelane_b32 v254, s0, 46
	s_mov_b32 s8, 0xc1d00000
	s_mov_b32 s10, 2.0
	v_writelane_b32 v254, s1, 47
	s_lshl_b64 s[0:1], s[28:29], 19
	v_writelane_b32 v254, s0, 48
	s_mov_b32 s5, 0xc1980000
	s_mov_b32 s7, 0xc1c80000
	v_writelane_b32 v254, s1, 49
	s_lshl_b64 s[0:1], s[26:27], 14
	v_writelane_b32 v254, s0, 50
	s_mov_b32 s9, 0xc1d80000
	s_mov_b32 s11, 0x40400000
	v_writelane_b32 v254, s1, 51
	s_mov_b32 s0, s26
	v_writelane_b32 v254, s0, 52
	v_mov_b32_e32 v227, 0x3e38aa3b
	s_mov_b32 s65, 0x5040100
	v_writelane_b32 v254, s1, 53
	s_lshl_b64 s[0:1], s[26:27], 19
	v_writelane_b32 v254, s0, 54
	s_mov_b32 s33, 0x42800000
	s_movk_i32 s2, 0x7fff
	v_writelane_b32 v254, s1, 55
	s_mov_b64 s[0:1], 0
	v_writelane_b32 v254, s0, 56
	s_mov_b64 s[34:35], 0x80
	s_mov_b64 s[74:75], 0x1100
	v_writelane_b32 v254, s1, 57
	v_writelane_b32 v254, s97, 58
	v_writelane_b32 v254, s94, 59
	s_mov_b32 s86, 0xbf600358
	s_mov_b32 s90, -1.0
	v_writelane_b32 v254, s95, 60
	v_writelane_b32 v254, s87, 61
	v_writelane_b32 v254, s80, 62
	s_branch .LBB0_14

.LBB0_860:
	v_readlane_b32 s28, v254, 56
	s_and_b32 s28, s28, 7
	s_cmp_eq_u32 s28, 4
	s_cselect_b32 s29, 1, 0
	s_cmp_eq_u32 s28, 6
	s_cselect_b32 s28, 1, s29
	s_cmp_eq_u32 s28, 0
	s_cbranch_scc1 .Lgb_decided
	v_readlane_b32 s29, v255, 20
	s_nop 0
	s_cmp_lg_u32 s29, 0
	s_cbranch_scc1 .Lgb_known
	s_mov_b64 s[26:27], 0x5000
	v_lshl_add_u64 v[12:13], v[2:3], 0, s[26:27]
	flat_load_dword v12, v[12:13] sc1
	s_waitcnt vmcnt(0) lgkmcnt(0)
	v_readfirstlane_b32 s29, v12
	s_nop 0
	s_cmp_eq_u32 s29, 0
	s_cselect_b32 s29, 1, 2
	s_nop 0
	v_writelane_b32 v255, s29, 20
.Lgb_known:
	s_cmp_eq_u32 s29, 1
	s_cselect_b32 s28, 1, 0
.Lgb_decided:
	v_readlane_b32 s0, v252, 10
	s_lshl_b32 s50, s0, 2
	v_lshl_add_u64 v[4:5], v[2:3], 0, s[50:51]
	v_add_co_u32_e32 v10, vcc, 0x1000, v4
	v_cvt_f32_u32_e32 v1, v8
	s_nop 0
	v_addc_co_u32_e32 v11, vcc, 0, v5, vcc
	s_cmp_eq_u32 s28, 1
	s_cbranch_scc0 .Lgb_noinv
	buffer_inv sc1
.Lgb_noinv:
	flat_atomic_add v7, v[10:11], v223 offset:1024 sc0
	v_rcp_iflag_f32_e32 v1, v1
	v_sub_u32_e32 v9, 0, v8
	v_mul_f32_e32 v1, 0x4f7ffffe, v1
	v_cvt_u32_f32_e32 v1, v1
	v_mul_lo_u32 v9, v9, v1
	v_mul_hi_u32 v9, v1, v9
	v_add_u32_e32 v1, v1, v9
	s_waitcnt vmcnt(0) lgkmcnt(0)
	v_mul_hi_u32 v1, v7, v1
	v_mul_lo_u32 v9, v1, v8
	v_sub_u32_e32 v9, v7, v9
	v_cmp_ge_u32_e32 vcc, v9, v8
	v_add_u32_e32 v10, 1, v1
	v_add_u32_e32 v7, 1, v7
	v_cndmask_b32_e32 v1, v1, v10, vcc
	v_sub_u32_e32 v10, v9, v8
	v_cndmask_b32_e32 v9, v9, v10, vcc
	v_cmp_ge_u32_e32 vcc, v9, v8
	v_add_u32_e32 v9, 1, v1
	s_nop 0
	v_cndmask_b32_e32 v1, v1, v9, vcc
	v_mad_u64_u32 v[8:9], s[0:1], v8, v1, v[8:9]
	s_mov_b64 s[26:27], 0x3000
	v_add_u32_e32 v9, 1, v1
	v_lshl_add_u64 v[10:11], v[2:3], 0, s[26:27]
	v_mul_lo_u32 v9, v9, v6
	s_cmp_eq_u32 s28, 1
	s_cbranch_scc0 .Lgb_full
	v_cmp_ne_u32_e32 vcc, v7, v8
	s_cbranch_vccnz .Lgb_l_arrived
	flat_atomic_add v[10:11], v223 offset:1024
.Lgb_l_arrived:
	v_mov_b32_e32 v9, v8
	s_mov_b64 s[26:27], 0x1000
	v_lshl_add_u64 v[10:11], v[4:5], 0, s[26:27]
	s_branch .Lgb_poll
.Lgb_full:
	v_cmp_ne_u32_e32 vcc, v7, v8
	s_cbranch_vccnz .Lgb_arrived
	buffer_wbl2 sc1
	s_waitcnt vmcnt(0)
	flat_atomic_add v[10:11], v223 offset:1024
	buffer_inv sc1
	s_branch .Lgb_poll
